# dilated attention: lean masked-score path for band-edge sub-tiles (interior tiles), on top of MLA body + phase-0 rotation
# speedup vs baseline: 1.0028x; 1.0028x over previous
.LBB0_705:
	s_andn2_b64 vcc, exec, s[10:11]
	s_cbranch_vccnz .LBB0_739
	s_cmp_lt_i32 s12, 0
	s_cbranch_scc1 .Lmslow_d0
	s_add_i32 s13, s12, 31
	s_cmp_ge_i32 s13, s20
	s_cbranch_scc1 .Lmslow_d0
	ds_read_b32 v32, v88 offset:0
	ds_read_b32 v33, v88 offset:4
	ds_read_b32 v34, v88 offset:8
	ds_read_b32 v35, v88 offset:12
	ds_read_b32 v36, v88 offset:32
	ds_read_b32 v37, v88 offset:36
	ds_read_b32 v38, v88 offset:40
	ds_read_b32 v39, v88 offset:44
	ds_read_b32 v40, v88 offset:64
	ds_read_b32 v41, v88 offset:68
	ds_read_b32 v42, v88 offset:72
	ds_read_b32 v43, v88 offset:76
	ds_read_b32 v44, v88 offset:96
	ds_read_b32 v45, v88 offset:100
	ds_read_b32 v46, v88 offset:104
	ds_read_b32 v47, v88 offset:108
	v_mov_b32_e32 v202, 0xff800000
	v_add_u32_e32 v200, s24, v87
	v_cmp_gt_u32_e32 vcc, s37, v200
	v_add_u32_e32 v203, 1, v200
	v_cmp_gt_u32_e64 s[30:31], s37, v203
	s_waitcnt lgkmcnt(0)
	v_fmac_f32_e32 v32, 0x3e38aa3b, v48
	v_cndmask_b32_e32 v32, v202, v32, vcc
	v_add_u32_e32 v201, 2, v200
	v_cmp_gt_u32_e32 vcc, s37, v201
	v_fmac_f32_e32 v33, 0x3e38aa3b, v49
	v_cndmask_b32_e64 v33, v202, v33, s[30:31]
	v_add_u32_e32 v203, 3, v200
	v_cmp_gt_u32_e64 s[30:31], s37, v203
	v_fmac_f32_e32 v34, 0x3e38aa3b, v50
	v_cndmask_b32_e32 v34, v202, v34, vcc
	v_add_u32_e32 v201, 8, v200
	v_cmp_gt_u32_e32 vcc, s37, v201
	v_fmac_f32_e32 v35, 0x3e38aa3b, v51
	v_cndmask_b32_e64 v35, v202, v35, s[30:31]
	v_add_u32_e32 v203, 9, v200
	v_cmp_gt_u32_e64 s[30:31], s37, v203
	v_fmac_f32_e32 v36, 0x3e38aa3b, v52
	v_cndmask_b32_e32 v36, v202, v36, vcc
	v_add_u32_e32 v201, 10, v200
	v_cmp_gt_u32_e32 vcc, s37, v201
	v_fmac_f32_e32 v37, 0x3e38aa3b, v53
	v_cndmask_b32_e64 v37, v202, v37, s[30:31]
	v_add_u32_e32 v203, 11, v200
	v_cmp_gt_u32_e64 s[30:31], s37, v203
	v_fmac_f32_e32 v38, 0x3e38aa3b, v54
	v_cndmask_b32_e32 v38, v202, v38, vcc
	v_add_u32_e32 v201, 16, v200
	v_cmp_gt_u32_e32 vcc, s37, v201
	v_fmac_f32_e32 v39, 0x3e38aa3b, v55
	v_cndmask_b32_e64 v39, v202, v39, s[30:31]
	v_add_u32_e32 v203, 17, v200
	v_cmp_gt_u32_e64 s[30:31], s37, v203
	v_fmac_f32_e32 v40, 0x3e38aa3b, v56
	v_cndmask_b32_e32 v40, v202, v40, vcc
	v_add_u32_e32 v201, 18, v200
	v_cmp_gt_u32_e32 vcc, s37, v201
	v_fmac_f32_e32 v41, 0x3e38aa3b, v57
	v_cndmask_b32_e64 v41, v202, v41, s[30:31]
	v_add_u32_e32 v203, 19, v200
	v_cmp_gt_u32_e64 s[30:31], s37, v203
	v_fmac_f32_e32 v42, 0x3e38aa3b, v58
	v_cndmask_b32_e32 v42, v202, v42, vcc
	v_add_u32_e32 v201, 24, v200
	v_cmp_gt_u32_e32 vcc, s37, v201
	v_fmac_f32_e32 v43, 0x3e38aa3b, v59
	v_cndmask_b32_e64 v43, v202, v43, s[30:31]
	v_add_u32_e32 v203, 25, v200
	v_cmp_gt_u32_e64 s[30:31], s37, v203
	v_fmac_f32_e32 v44, 0x3e38aa3b, v60
	v_cndmask_b32_e32 v44, v202, v44, vcc
	v_add_u32_e32 v201, 26, v200
	v_cmp_gt_u32_e32 vcc, s37, v201
	v_fmac_f32_e32 v45, 0x3e38aa3b, v61
	v_cndmask_b32_e64 v45, v202, v45, s[30:31]
	v_add_u32_e32 v203, 27, v200
	v_cmp_gt_u32_e64 s[30:31], s37, v203
	v_fmac_f32_e32 v46, 0x3e38aa3b, v62
	v_cndmask_b32_e32 v46, v202, v46, vcc
	v_fmac_f32_e32 v47, 0x3e38aa3b, v63
	v_cndmask_b32_e64 v47, v202, v47, s[30:31]
	s_branch .LBB0_739
.Lmslow_d0:
	v_add_u32_e32 v94, s24, v89
	s_cmp_gt_i32 s12, -1
	v_add_u32_e32 v95, s24, v87
	v_subrev_u32_e32 v32, 64, v94
	s_cselect_b64 s[10:11], -1, 0
	v_cmp_gt_u32_e32 vcc, s37, v95
	s_and_b64 s[12:13], s[10:11], vcc
	v_cmp_gt_i32_e32 vcc, s20, v32
	s_and_b64 s[30:31], s[12:13], vcc
	v_mov_b32_e32 v33, 0xff800000
	v_mov_b32_e32 v32, 0xff800000
	s_and_saveexec_b64 s[12:13], s[30:31]
	s_cbranch_execz .LBB0_708
	v_add_u32_e32 v32, 0, v88
	ds_read_b32 v32, v32
	s_waitcnt lgkmcnt(0)
	v_fmac_f32_e32 v32, 0x3e38aa3b, v48

.LBB0_749:
	s_andn2_b64 vcc, exec, s[10:11]
	s_cbranch_vccnz .LBB0_783
	s_cmp_lt_i32 s12, 0
	s_cbranch_scc1 .Lmslow_d1
	s_add_i32 s13, s12, 31
	s_cmp_ge_i32 s13, s20
	s_cbranch_scc1 .Lmslow_d1
	ds_read_b32 v32, v88 offset:128
	ds_read_b32 v33, v88 offset:132
	ds_read_b32 v34, v88 offset:136
	ds_read_b32 v35, v88 offset:140
	ds_read_b32 v36, v88 offset:160
	ds_read_b32 v37, v88 offset:164
	ds_read_b32 v38, v88 offset:168
	ds_read_b32 v39, v88 offset:172
	ds_read_b32 v40, v88 offset:192
	ds_read_b32 v41, v88 offset:196
	ds_read_b32 v42, v88 offset:200
	ds_read_b32 v43, v88 offset:204
	ds_read_b32 v44, v88 offset:224
	ds_read_b32 v45, v88 offset:228
	ds_read_b32 v46, v88 offset:232
	ds_read_b32 v47, v88 offset:236
	v_mov_b32_e32 v202, 0xff800000
	v_add_u32_e32 v200, s24, v87
	v_add_u32_e32 v201, 32, v200
	v_cmp_gt_u32_e32 vcc, s37, v201
	v_add_u32_e32 v203, 33, v200
	v_cmp_gt_u32_e64 s[30:31], s37, v203
	s_waitcnt lgkmcnt(0)
	v_fmac_f32_e32 v32, 0x3e38aa3b, v48
	v_cndmask_b32_e32 v32, v202, v32, vcc
	v_add_u32_e32 v201, 34, v200
	v_cmp_gt_u32_e32 vcc, s37, v201
	v_fmac_f32_e32 v33, 0x3e38aa3b, v49
	v_cndmask_b32_e64 v33, v202, v33, s[30:31]
	v_add_u32_e32 v203, 35, v200
	v_cmp_gt_u32_e64 s[30:31], s37, v203
	v_fmac_f32_e32 v34, 0x3e38aa3b, v50
	v_cndmask_b32_e32 v34, v202, v34, vcc
	v_add_u32_e32 v201, 40, v200
	v_cmp_gt_u32_e32 vcc, s37, v201
	v_fmac_f32_e32 v35, 0x3e38aa3b, v51
	v_cndmask_b32_e64 v35, v202, v35, s[30:31]
	v_add_u32_e32 v203, 41, v200
	v_cmp_gt_u32_e64 s[30:31], s37, v203
	v_fmac_f32_e32 v36, 0x3e38aa3b, v52
	v_cndmask_b32_e32 v36, v202, v36, vcc
	v_add_u32_e32 v201, 42, v200
	v_cmp_gt_u32_e32 vcc, s37, v201
	v_fmac_f32_e32 v37, 0x3e38aa3b, v53
	v_cndmask_b32_e64 v37, v202, v37, s[30:31]
	v_add_u32_e32 v203, 43, v200
	v_cmp_gt_u32_e64 s[30:31], s37, v203
	v_fmac_f32_e32 v38, 0x3e38aa3b, v54
	v_cndmask_b32_e32 v38, v202, v38, vcc
	v_add_u32_e32 v201, 48, v200
	v_cmp_gt_u32_e32 vcc, s37, v201
	v_fmac_f32_e32 v39, 0x3e38aa3b, v55
	v_cndmask_b32_e64 v39, v202, v39, s[30:31]
	v_add_u32_e32 v203, 49, v200
	v_cmp_gt_u32_e64 s[30:31], s37, v203
	v_fmac_f32_e32 v40, 0x3e38aa3b, v56
	v_cndmask_b32_e32 v40, v202, v40, vcc
	v_add_u32_e32 v201, 50, v200
	v_cmp_gt_u32_e32 vcc, s37, v201
	v_fmac_f32_e32 v41, 0x3e38aa3b, v57
	v_cndmask_b32_e64 v41, v202, v41, s[30:31]
	v_add_u32_e32 v203, 51, v200
	v_cmp_gt_u32_e64 s[30:31], s37, v203
	v_fmac_f32_e32 v42, 0x3e38aa3b, v58
	v_cndmask_b32_e32 v42, v202, v42, vcc
	v_add_u32_e32 v201, 56, v200
	v_cmp_gt_u32_e32 vcc, s37, v201
	v_fmac_f32_e32 v43, 0x3e38aa3b, v59
	v_cndmask_b32_e64 v43, v202, v43, s[30:31]
	v_add_u32_e32 v203, 57, v200
	v_cmp_gt_u32_e64 s[30:31], s37, v203
	v_fmac_f32_e32 v44, 0x3e38aa3b, v60
	v_cndmask_b32_e32 v44, v202, v44, vcc
	v_add_u32_e32 v201, 58, v200
	v_cmp_gt_u32_e32 vcc, s37, v201
	v_fmac_f32_e32 v45, 0x3e38aa3b, v61
	v_cndmask_b32_e64 v45, v202, v45, s[30:31]
	v_add_u32_e32 v203, 59, v200
	v_cmp_gt_u32_e64 s[30:31], s37, v203
	v_fmac_f32_e32 v46, 0x3e38aa3b, v62
	v_cndmask_b32_e32 v46, v202, v46, vcc
	v_fmac_f32_e32 v47, 0x3e38aa3b, v63
	v_cndmask_b32_e64 v47, v202, v47, s[30:31]
	s_branch .LBB0_783
.Lmslow_d1:
	v_add_u32_e32 v95, s24, v87
	v_add_u32_e32 v93, s24, v89
	s_cmp_gt_i32 s12, -1
	v_add_u32_e32 v33, 32, v95
	v_subrev_u32_e32 v32, 32, v93
	s_cselect_b64 s[10:11], -1, 0
	v_cmp_gt_u32_e32 vcc, s37, v33
	s_and_b64 s[12:13], s[10:11], vcc
	v_cmp_gt_i32_e32 vcc, s20, v32
	s_and_b64 s[28:29], s[12:13], vcc
	v_mov_b32_e32 v33, 0xff800000
	v_mov_b32_e32 v32, 0xff800000
	s_and_saveexec_b64 s[12:13], s[28:29]
	s_cbranch_execz .LBB0_752
	v_add_u32_e32 v32, 0x1c080, v92
	ds_read_b32 v32, v32
	s_waitcnt lgkmcnt(0)
	v_fmac_f32_e32 v32, 0x3e38aa3b, v48
